# baseline (speedup 1.0000x reference)
; #define PG8_STAGE(bufoff, gbase, voff) do { _Pragma("unroll") for (int _i = 0; _i < 2; ++_i) \
;         __builtin_amdgcn_global_load_lds((const unsigned*)((const char*)(gbase) + (voff)[_i]), (LAS unsigned*)(lds + (bufoff) + ldsw + _i * 8192), 16, 0, 0); } while (0)
; #define PG8_LDA(dst, b, h) do { _Pragma("unroll") for (int m = 0; m < 4; ++m) _Pragma("unroll") for (int k = 0; k < 2; ++k) dst[m][k] = *(const LAS bf16x8*)(lds + PG8_SA(b, h) + aoff + m * 2048 + k * 1024); } while (0)
; #define PG8_LDB(dst, b, h) do { _Pragma("unroll") for (int n = 0; n < 2; ++n) _Pragma("unroll") for (int k = 0; k < 2; ++k) dst[n][k] = *(const LAS bf16x8*)(lds + PG8_SB(b, h) + boff + n * 2048 + k * 1024); } while (0)
; #define PG8_WAIT_V(n) asm volatile("s_waitcnt vmcnt(" #n ")" ::: "memory")
; #define PG8_WAIT_L(n) asm volatile("s_waitcnt lgkmcnt(" #n ")" ::: "memory")
; #define PG8_BAR __builtin_amdgcn_s_barrier()
; #define PG8_SCHED __builtin_amdgcn_sched_barrier(0)
; template <class Epi, class Pre, bool AG = false>
; __device__ __forceinline__ void gemm_phase(LAS unsigned char* lds, const Gemm g, const StaticOrder& S, const Epi& E, const Pre& P) {
;     ...
;         const bool has_next = S.next(ui + 1, nxt);
;         const char* nA = has_next ? (const char*)g.A + (size_t)nxt.pm * tstepA : cA; const char* nB = has_next ? (const char*)g.Bt + (size_t)nxt.pn * tstep : cB;
;         for (int t = 0; t < nt; t += 2) {
;             const bool last = (t == nt - 2);
;             const char* a1 = cA + (size_t)(t + 1) * kstepA;
;             const char* a2 = last ? nA : cA + (size_t)(t + 2) * kstepA; const char* b2 = last ? nB : cB + (size_t)(t + 2) * kstep;
;             const char* a3 = a2 + kstepA; const char* b3 = b2 + kstep;
;             if constexpr (Epi::MIDK) { if (t == E.midk_t) E.mid(acc, cur, ui, wr, wc, fr, fq); }
;             PG8_LDB(B0, 0, 0); PG8_LDB(B1, 0, 1); PG8_SCHED; PG8_LDA(At, 0, 0); PG8_STAGE(PG8_SA(1, 1), a1 + hstepA, voffA);
;             PG8_WAIT_V(8); PG8_WAIT_L(0); PG8_BAR; PG8_MMA(0, 0, At, B0); PG8_MMA(0, 1, At, B1); PG8_BAR; PG8_SCHED;
;             PG8_LDA(At, 0, 1); PG8_STAGE(PG8_SB(0, 0), b2, voffB); PG8_STAGE(PG8_SB(0, 1), b2 + hstep, voffB); PG8_STAGE(PG8_SA(0, 0), a2, voffA);
;             PG8_WAIT_V(8); PG8_WAIT_L(0); PG8_BAR; PG8_MMA(1, 0, At, B0); PG8_MMA(1, 1, At, B1); PG8_BAR; PG8_SCHED;
.LBB0_211:
	s_ashr_i32 s27, s26, 31
	s_lshl_b64 s[12:13], s[26:27], 19
	s_add_u32 s28, s20, s12
	s_addc_u32 s29, s24, s13
	s_and_b64 s[12:13], s[6:7], exec
	s_cselect_b32 s12, s29, s45
	s_cselect_b32 s13, s28, s44
	s_ashr_i32 s17, s16, 31
	s_lshl_b64 s[42:43], s[16:17], 19
	s_add_u32 s42, s25, s42
	s_addc_u32 s43, s30, s43
	s_and_b64 s[54:55], s[6:7], exec
	s_cselect_b32 s17, s43, s47
	s_cselect_b32 s27, s42, s46
	s_add_u32 s44, s44, 0x40080
	s_addc_u32 s45, s45, 0
	s_add_u32 s76, s46, 0x100
	s_addc_u32 s77, s47, 0
	s_mov_b32 s79, -2
	s_add_u32 s46, s44, 0xfffc0080
	s_addc_u32 s47, s45, -1
	s_add_i32 s84, 0, 0x10000
	s_cmp_eq_u32 s79, 12
	s_cselect_b32 s55, s12, s47
	s_cselect_b32 s54, s13, s46
	s_cselect_b32 s47, s17, s77
	s_cselect_b32 s46, s27, s76
	s_add_i32 s86, 0, 0x14000
	v_add_u32_e32 v154, s84, v148
	v_add_u32_e32 v170, s86, v148
	ds_read_b128 v[140:143], v154
	ds_read_b128 v[144:147], v154 offset:1024
	ds_read_b128 v[150:153], v154 offset:2048
	ds_read_b128 v[154:157], v154 offset:3072
	ds_read_b128 v[158:161], v170
	ds_read_b128 v[162:165], v170 offset:1024
	ds_read_b128 v[166:169], v170 offset:2048
	ds_read_b128 v[170:173], v170 offset:3072
	v_lshl_add_u64 v[178:179], s[44:45], 0, v[0:1]
	s_add_i32 m0, s38, 0xc000
	ds_read_b128 v[174:177], v149
	ds_read_b128 v[194:197], v149 offset:1024
	ds_read_b128 v[198:201], v149 offset:2048
	ds_read_b128 v[202:205], v149 offset:3072
	ds_read_b128 v[206:209], v149 offset:4096
	ds_read_b128 v[210:213], v149 offset:5120
	ds_read_b128 v[214:217], v149 offset:6144
	ds_read_b128 v[218:221], v149 offset:7168
	global_load_lds_dwordx4 v[178:179], off
	v_lshl_add_u64 v[178:179], s[44:45], 0, v[138:139]
	s_add_i32 m0, s38, 0xe000
	s_nop 0
	global_load_lds_dwordx4 v[178:179], off
	s_waitcnt vmcnt(8)
	s_waitcnt lgkmcnt(0)
	s_barrier
	s_setprio 1
	s_waitcnt lgkmcnt(0)
	v_mfma_f32_16x16x32_bf16 v[122:125], v[140:143], v[174:177], 0
	v_mfma_f32_16x16x32_bf16 v[114:117], v[150:153], v[174:177], 0
	v_mfma_f32_16x16x32_bf16 v[106:109], v[140:143], v[198:201], 0
	v_mfma_f32_16x16x32_bf16 v[98:101], v[150:153], v[198:201], 0
	v_mfma_f32_16x16x32_bf16 v[90:93], v[140:143], v[206:209], 0
	v_mfma_f32_16x16x32_bf16 v[82:85], v[150:153], v[206:209], 0
	v_mfma_f32_16x16x32_bf16 v[74:77], v[140:143], v[214:217], 0
	v_mfma_f32_16x16x32_bf16 v[66:69], v[150:153], v[214:217], 0
	v_mfma_f32_16x16x32_bf16 v[122:125], v[144:147], v[194:197], v[122:125]
	v_mfma_f32_16x16x32_bf16 v[114:117], v[154:157], v[194:197], v[114:117]
	v_mfma_f32_16x16x32_bf16 v[106:109], v[144:147], v[202:205], v[106:109]
	v_mfma_f32_16x16x32_bf16 v[98:101], v[154:157], v[202:205], v[98:101]
	v_mfma_f32_16x16x32_bf16 v[90:93], v[144:147], v[210:213], v[90:93]
	v_mfma_f32_16x16x32_bf16 v[82:85], v[154:157], v[210:213], v[82:85]
	v_mfma_f32_16x16x32_bf16 v[74:77], v[144:147], v[218:221], v[74:77]
	v_mfma_f32_16x16x32_bf16 v[66:69], v[154:157], v[218:221], v[66:69]
	s_setprio 0
	s_setprio 1
	v_mfma_f32_16x16x32_bf16 v[126:129], v[158:161], v[174:177], 0
	v_mfma_f32_16x16x32_bf16 v[118:121], v[166:169], v[174:177], 0
	v_mfma_f32_16x16x32_bf16 v[110:113], v[158:161], v[198:201], 0
	v_mfma_f32_16x16x32_bf16 v[102:105], v[166:169], v[198:201], 0
	v_mfma_f32_16x16x32_bf16 v[94:97], v[158:161], v[206:209], 0
	v_mfma_f32_16x16x32_bf16 v[86:89], v[166:169], v[206:209], 0
	v_mfma_f32_16x16x32_bf16 v[78:81], v[158:161], v[214:217], 0
	v_mfma_f32_16x16x32_bf16 v[70:73], v[166:169], v[214:217], 0
	v_mfma_f32_16x16x32_bf16 v[126:129], v[162:165], v[194:197], v[126:129]
	v_mfma_f32_16x16x32_bf16 v[118:121], v[170:173], v[194:197], v[118:121]
	v_mfma_f32_16x16x32_bf16 v[110:113], v[162:165], v[202:205], v[110:113]
	v_mfma_f32_16x16x32_bf16 v[102:105], v[170:173], v[202:205], v[102:105]
	v_mfma_f32_16x16x32_bf16 v[94:97], v[162:165], v[210:213], v[94:97]
	v_mfma_f32_16x16x32_bf16 v[86:89], v[170:173], v[210:213], v[86:89]
	v_mfma_f32_16x16x32_bf16 v[78:81], v[162:165], v[218:221], v[78:81]
	v_mfma_f32_16x16x32_bf16 v[70:73], v[170:173], v[218:221], v[70:73]
	s_setprio 0
	s_barrier
	s_add_i32 s84, s84, s31
	v_lshl_add_u64 v[178:179], s[46:47], 0, v[134:135]
	s_mov_b32 m0, s84
	ds_read_b128 v[174:177], v149 offset:16384
	ds_read_b128 v[194:197], v149 offset:17408
	ds_read_b128 v[198:201], v149 offset:18432
	ds_read_b128 v[202:205], v149 offset:19456
	ds_read_b128 v[206:209], v149 offset:20480
	ds_read_b128 v[210:213], v149 offset:21504
	ds_read_b128 v[214:217], v149 offset:22528
	ds_read_b128 v[218:221], v149 offset:23552
	global_load_lds_dwordx4 v[178:179], off
	s_add_i32 m0, s84, 0x2000
	s_add_u32 s84, s46, 0x40000
	v_lshl_add_u64 v[180:181], s[46:47], 0, v[130:131]
	s_addc_u32 s85, s47, 0
	s_add_i32 s86, s86, s31
	global_load_lds_dwordx4 v[180:181], off
	v_lshl_add_u64 v[182:183], s[84:85], 0, v[134:135]
	s_mov_b32 m0, s86
	v_lshl_add_u64 v[188:189], s[54:55], 0, v[132:133]
	global_load_lds_dwordx4 v[182:183], off
	v_lshl_add_u64 v[182:183], s[84:85], 0, v[130:131]
	s_add_i32 m0, s86, 0x2000
	s_nop 0
	global_load_lds_dwordx4 v[182:183], off
	v_lshl_add_u64 v[182:183], s[54:55], 0, v[136:137]
	s_mov_b32 m0, s38
	s_nop 0
	global_load_lds_dwordx4 v[182:183], off
	s_mov_b32 m0, s48
	s_nop 0
	global_load_lds_dwordx4 v[188:189], off
	s_waitcnt vmcnt(8)
	s_waitcnt lgkmcnt(0)
	s_barrier
; #define PG8_STAGE(bufoff, gbase, voff) do { _Pragma("unroll") for (int _i = 0; _i < 2; ++_i) \
;         __builtin_amdgcn_global_load_lds((const unsigned*)((const char*)(gbase) + (voff)[_i]), (LAS unsigned*)(lds + (bufoff) + ldsw + _i * 8192), 16, 0, 0); } while (0)
; #define PG8_LDA(dst, b, h) do { _Pragma("unroll") for (int m = 0; m < 4; ++m) _Pragma("unroll") for (int k = 0; k < 2; ++k) dst[m][k] = *(const LAS bf16x8*)(lds + PG8_SA(b, h) + aoff + m * 2048 + k * 1024); } while (0)
; #define PG8_LDB(dst, b, h) do { _Pragma("unroll") for (int n = 0; n < 2; ++n) _Pragma("unroll") for (int k = 0; k < 2; ++k) dst[n][k] = *(const LAS bf16x8*)(lds + PG8_SB(b, h) + boff + n * 2048 + k * 1024); } while (0)
; #define PG8_MMA(ai, bj, At, Bt) do { __builtin_amdgcn_s_setprio(1); _Pragma("unroll") for (int m = 0; m < 4; ++m) _Pragma("unroll") for (int n = 0; n < 2; ++n) _Pragma("unroll") for (int k = 0; k < 2; ++k) \
;         acc[ai][bj][m][n] = __builtin_amdgcn_mfma_f32_16x16x32_bf16(Bt[n][k], At[m][k], acc[ai][bj][m][n], 0, 0, 0); __builtin_amdgcn_s_setprio(0); } while (0)
; #define PG8_WAIT_V(n) asm volatile("s_waitcnt vmcnt(" #n ")" ::: "memory")
; #define PG8_WAIT_L(n) asm volatile("s_waitcnt lgkmcnt(" #n ")" ::: "memory")
; #define PG8_BAR __builtin_amdgcn_s_barrier()
; #define PG8_SCHED __builtin_amdgcn_sched_barrier(0)
; template <class Epi, class Pre, bool AG = false>
; __device__ __forceinline__ void gemm_phase(LAS unsigned char* lds, const Gemm g, const StaticOrder& S, const Epi& E, const Pre& P) {
;     ...
;             PG8_WAIT_V(8); PG8_WAIT_L(0); PG8_BAR; PG8_MMA(1, 0, At, B0); PG8_MMA(1, 1, At, B1); PG8_BAR; PG8_SCHED;
;             PG8_LDB(B0, 1, 0); PG8_LDB(B1, 1, 1); PG8_SCHED; PG8_LDA(At, 1, 0); PG8_STAGE(PG8_SA(0, 1), a2 + hstepA, voffA);
;             PG8_WAIT_V(8); PG8_WAIT_L(0); PG8_BAR; PG8_MMA(0, 0, At, B0); PG8_MMA(0, 1, At, B1); PG8_BAR; PG8_SCHED;
	s_setprio 1
	s_waitcnt lgkmcnt(0)
	v_mfma_f32_16x16x32_bf16 v[58:61], v[140:143], v[174:177], 0
	v_mfma_f32_16x16x32_bf16 v[50:53], v[150:153], v[174:177], 0
	v_mfma_f32_16x16x32_bf16 v[42:45], v[140:143], v[198:201], 0
	v_mfma_f32_16x16x32_bf16 v[34:37], v[150:153], v[198:201], 0
	v_mfma_f32_16x16x32_bf16 v[26:29], v[140:143], v[206:209], 0
	v_mfma_f32_16x16x32_bf16 v[18:21], v[150:153], v[206:209], 0
	v_mfma_f32_16x16x32_bf16 v[10:13], v[140:143], v[214:217], 0
	v_mfma_f32_16x16x32_bf16 v[6:9], v[150:153], v[214:217], 0
	v_mfma_f32_16x16x32_bf16 v[58:61], v[144:147], v[194:197], v[58:61]
	v_mfma_f32_16x16x32_bf16 v[50:53], v[154:157], v[194:197], v[50:53]
	v_mfma_f32_16x16x32_bf16 v[42:45], v[144:147], v[202:205], v[42:45]
	v_mfma_f32_16x16x32_bf16 v[34:37], v[154:157], v[202:205], v[34:37]
	v_mfma_f32_16x16x32_bf16 v[26:29], v[144:147], v[210:213], v[26:29]
	v_mfma_f32_16x16x32_bf16 v[18:21], v[154:157], v[210:213], v[18:21]
	v_mfma_f32_16x16x32_bf16 v[10:13], v[144:147], v[218:221], v[10:13]
	v_mfma_f32_16x16x32_bf16 v[6:9], v[154:157], v[218:221], v[6:9]
	s_setprio 0
	s_setprio 1
	v_mfma_f32_16x16x32_bf16 v[62:65], v[158:161], v[174:177], 0
	v_mfma_f32_16x16x32_bf16 v[54:57], v[166:169], v[174:177], 0
	v_mfma_f32_16x16x32_bf16 v[46:49], v[158:161], v[198:201], 0
	v_mfma_f32_16x16x32_bf16 v[38:41], v[166:169], v[198:201], 0
	v_mfma_f32_16x16x32_bf16 v[30:33], v[158:161], v[206:209], 0
	v_mfma_f32_16x16x32_bf16 v[22:25], v[166:169], v[206:209], 0
	v_mfma_f32_16x16x32_bf16 v[14:17], v[158:161], v[214:217], 0
	v_mfma_f32_16x16x32_bf16 v[2:5], v[166:169], v[214:217], 0
	v_mfma_f32_16x16x32_bf16 v[62:65], v[162:165], v[194:197], v[62:65]
	v_mfma_f32_16x16x32_bf16 v[54:57], v[170:173], v[194:197], v[54:57]
	v_mfma_f32_16x16x32_bf16 v[46:49], v[162:165], v[202:205], v[46:49]
	v_mfma_f32_16x16x32_bf16 v[38:41], v[170:173], v[202:205], v[38:41]
	v_mfma_f32_16x16x32_bf16 v[30:33], v[162:165], v[210:213], v[30:33]
	v_mfma_f32_16x16x32_bf16 v[22:25], v[170:173], v[210:213], v[22:25]
	v_mfma_f32_16x16x32_bf16 v[14:17], v[162:165], v[218:221], v[14:17]
	v_mfma_f32_16x16x32_bf16 v[2:5], v[170:173], v[218:221], v[2:5]
	s_setprio 0
	s_barrier
	s_add_i32 s84, 0, 0x18000
	s_add_i32 s85, 0, 0x1c000
	v_add_u32_e32 v154, s84, v148
	v_add_u32_e32 v170, s85, v148
	ds_read_b128 v[140:143], v154
	ds_read_b128 v[144:147], v154 offset:1024
	ds_read_b128 v[150:153], v154 offset:2048
	ds_read_b128 v[154:157], v154 offset:3072
	ds_read_b128 v[158:161], v170
	ds_read_b128 v[162:165], v170 offset:1024
	ds_read_b128 v[166:169], v170 offset:2048
	ds_read_b128 v[170:173], v170 offset:3072
	s_add_u32 s54, s54, 0x40000
	s_addc_u32 s55, s55, 0
	s_mov_b32 m0, s49
	v_lshl_add_u64 v[190:191], s[54:55], 0, v[136:137]
	ds_read_b128 v[174:177], v149 offset:32768
	ds_read_b128 v[194:197], v149 offset:33792
	ds_read_b128 v[198:201], v149 offset:34816
	ds_read_b128 v[202:205], v149 offset:35840
	ds_read_b128 v[206:209], v149 offset:36864
	ds_read_b128 v[210:213], v149 offset:37888
	ds_read_b128 v[214:217], v149 offset:38912
	ds_read_b128 v[218:221], v149 offset:39936
	global_load_lds_dwordx4 v[190:191], off
	v_lshl_add_u64 v[190:191], s[54:55], 0, v[132:133]
	s_mov_b32 m0, s53
	s_nop 0
	global_load_lds_dwordx4 v[190:191], off
	s_waitcnt vmcnt(8)
	s_waitcnt lgkmcnt(0)
	s_barrier
	s_setprio 1
	s_waitcnt lgkmcnt(0)
	v_mfma_f32_16x16x32_bf16 v[122:125], v[140:143], v[174:177], v[122:125]
	v_mfma_f32_16x16x32_bf16 v[114:117], v[150:153], v[174:177], v[114:117]
	v_mfma_f32_16x16x32_bf16 v[106:109], v[140:143], v[198:201], v[106:109]
	v_mfma_f32_16x16x32_bf16 v[98:101], v[150:153], v[198:201], v[98:101]
	v_mfma_f32_16x16x32_bf16 v[90:93], v[140:143], v[206:209], v[90:93]
	v_mfma_f32_16x16x32_bf16 v[82:85], v[150:153], v[206:209], v[82:85]
	v_mfma_f32_16x16x32_bf16 v[74:77], v[140:143], v[214:217], v[74:77]
	v_mfma_f32_16x16x32_bf16 v[66:69], v[150:153], v[214:217], v[66:69]
	v_mfma_f32_16x16x32_bf16 v[122:125], v[144:147], v[194:197], v[122:125]
	v_mfma_f32_16x16x32_bf16 v[114:117], v[154:157], v[194:197], v[114:117]
	v_mfma_f32_16x16x32_bf16 v[106:109], v[144:147], v[202:205], v[106:109]
	v_mfma_f32_16x16x32_bf16 v[98:101], v[154:157], v[202:205], v[98:101]
	v_mfma_f32_16x16x32_bf16 v[90:93], v[144:147], v[210:213], v[90:93]
	v_mfma_f32_16x16x32_bf16 v[82:85], v[154:157], v[210:213], v[82:85]
	v_mfma_f32_16x16x32_bf16 v[74:77], v[144:147], v[218:221], v[74:77]
	v_mfma_f32_16x16x32_bf16 v[66:69], v[154:157], v[218:221], v[66:69]
	s_setprio 0
	s_setprio 1
	v_mfma_f32_16x16x32_bf16 v[126:129], v[158:161], v[174:177], v[126:129]
	v_mfma_f32_16x16x32_bf16 v[118:121], v[166:169], v[174:177], v[118:121]
	v_mfma_f32_16x16x32_bf16 v[110:113], v[158:161], v[198:201], v[110:113]
	v_mfma_f32_16x16x32_bf16 v[102:105], v[166:169], v[198:201], v[102:105]
	v_mfma_f32_16x16x32_bf16 v[94:97], v[158:161], v[206:209], v[94:97]
	v_mfma_f32_16x16x32_bf16 v[86:89], v[166:169], v[206:209], v[86:89]
	v_mfma_f32_16x16x32_bf16 v[78:81], v[158:161], v[214:217], v[78:81]
	v_mfma_f32_16x16x32_bf16 v[70:73], v[166:169], v[214:217], v[70:73]
	v_mfma_f32_16x16x32_bf16 v[126:129], v[162:165], v[194:197], v[126:129]
	v_mfma_f32_16x16x32_bf16 v[118:121], v[170:173], v[194:197], v[118:121]
	v_mfma_f32_16x16x32_bf16 v[110:113], v[162:165], v[202:205], v[110:113]
	v_mfma_f32_16x16x32_bf16 v[102:105], v[170:173], v[202:205], v[102:105]
	v_mfma_f32_16x16x32_bf16 v[94:97], v[162:165], v[210:213], v[94:97]
	v_mfma_f32_16x16x32_bf16 v[86:89], v[170:173], v[210:213], v[86:89]
	v_mfma_f32_16x16x32_bf16 v[78:81], v[162:165], v[218:221], v[78:81]
	v_mfma_f32_16x16x32_bf16 v[70:73], v[170:173], v[218:221], v[70:73]
	s_setprio 0
	s_barrier
; #define PG8_STAGE(bufoff, gbase, voff) do { _Pragma("unroll") for (int _i = 0; _i < 2; ++_i) \
;         __builtin_amdgcn_global_load_lds((const unsigned*)((const char*)(gbase) + (voff)[_i]), (LAS unsigned*)(lds + (bufoff) + ldsw + _i * 8192), 16, 0, 0); } while (0)
; #define PG8_LDA(dst, b, h) do { _Pragma("unroll") for (int m = 0; m < 4; ++m) _Pragma("unroll") for (int k = 0; k < 2; ++k) dst[m][k] = *(const LAS bf16x8*)(lds + PG8_SA(b, h) + aoff + m * 2048 + k * 1024); } while (0)
; #define PG8_MMA(ai, bj, At, Bt) do { __builtin_amdgcn_s_setprio(1); _Pragma("unroll") for (int m = 0; m < 4; ++m) _Pragma("unroll") for (int n = 0; n < 2; ++n) _Pragma("unroll") for (int k = 0; k < 2; ++k) \
;         acc[ai][bj][m][n] = __builtin_amdgcn_mfma_f32_16x16x32_bf16(Bt[n][k], At[m][k], acc[ai][bj][m][n], 0, 0, 0); __builtin_amdgcn_s_setprio(0); } while (0)
; #define PG8_WAIT_V(n) asm volatile("s_waitcnt vmcnt(" #n ")" ::: "memory")
; #define PG8_WAIT_L(n) asm volatile("s_waitcnt lgkmcnt(" #n ")" ::: "memory")
; #define PG8_BAR __builtin_amdgcn_s_barrier()
; #define PG8_SCHED __builtin_amdgcn_sched_barrier(0)
; template <class Epi, class Pre, bool AG = false>
; __device__ __forceinline__ void gemm_phase(LAS unsigned char* lds, const Gemm g, const StaticOrder& S, const Epi& E, const Pre& P) {
;     ...
;         for (int t = 0; t < nt; t += 2) {
;     ...
;             PG8_LDA(At, 1, 1); PG8_STAGE(PG8_SB(1, 0), b3, voffB); PG8_STAGE(PG8_SB(1, 1), b3 + hstep, voffB); PG8_STAGE(PG8_SA(1, 0), a3, voffA);
;             PG8_WAIT_V(8); PG8_WAIT_L(0); PG8_BAR; PG8_MMA(1, 0, At, B0); PG8_MMA(1, 1, At, B1); PG8_BAR; PG8_SCHED;
	s_add_i32 s54, s84, s31
	v_lshl_add_u64 v[178:179], v[178:179], 0, s[66:67]
	s_mov_b32 m0, s54
	ds_read_b128 v[174:177], v149 offset:49152
	ds_read_b128 v[194:197], v149 offset:50176
	ds_read_b128 v[198:201], v149 offset:51200
	ds_read_b128 v[202:205], v149 offset:52224
	ds_read_b128 v[206:209], v149 offset:53248
	ds_read_b128 v[210:213], v149 offset:54272
	ds_read_b128 v[214:217], v149 offset:55296
	ds_read_b128 v[218:221], v149 offset:56320
	global_load_lds_dwordx4 v[178:179], off
	s_add_i32 m0, s54, 0x2000
	s_add_u32 s46, s46, 0x40080
	v_lshl_add_u64 v[178:179], v[180:181], 0, s[66:67]
	s_addc_u32 s47, s47, 0
	s_add_i32 s54, s85, s31
	global_load_lds_dwordx4 v[178:179], off
	v_lshl_add_u64 v[178:179], s[46:47], 0, v[134:135]
	s_mov_b32 m0, s54
	s_nop 0
	global_load_lds_dwordx4 v[178:179], off
	v_lshl_add_u64 v[178:179], s[46:47], 0, v[130:131]
	s_add_i32 m0, s54, 0x2000
	s_nop 0
	global_load_lds_dwordx4 v[178:179], off
	v_lshl_add_u64 v[178:179], v[182:183], 0, s[66:67]
	s_mov_b32 m0, s58
	s_nop 0
	global_load_lds_dwordx4 v[178:179], off
	v_lshl_add_u64 v[178:179], v[188:189], 0, s[66:67]
	s_mov_b32 m0, s59
	s_nop 0
	global_load_lds_dwordx4 v[178:179], off
	s_waitcnt vmcnt(8)
	s_waitcnt lgkmcnt(0)
	s_barrier
	s_setprio 1
	s_waitcnt lgkmcnt(0)
	v_mfma_f32_16x16x32_bf16 v[58:61], v[140:143], v[174:177], v[58:61]
	v_mfma_f32_16x16x32_bf16 v[50:53], v[150:153], v[174:177], v[50:53]
	v_mfma_f32_16x16x32_bf16 v[42:45], v[140:143], v[198:201], v[42:45]
	v_mfma_f32_16x16x32_bf16 v[34:37], v[150:153], v[198:201], v[34:37]
	v_mfma_f32_16x16x32_bf16 v[26:29], v[140:143], v[206:209], v[26:29]
	v_mfma_f32_16x16x32_bf16 v[18:21], v[150:153], v[206:209], v[18:21]
	v_mfma_f32_16x16x32_bf16 v[10:13], v[140:143], v[214:217], v[10:13]
	v_mfma_f32_16x16x32_bf16 v[6:9], v[150:153], v[214:217], v[6:9]
	v_mfma_f32_16x16x32_bf16 v[58:61], v[144:147], v[194:197], v[58:61]
	v_mfma_f32_16x16x32_bf16 v[50:53], v[154:157], v[194:197], v[50:53]
	v_mfma_f32_16x16x32_bf16 v[42:45], v[144:147], v[202:205], v[42:45]
	v_mfma_f32_16x16x32_bf16 v[34:37], v[154:157], v[202:205], v[34:37]
	v_mfma_f32_16x16x32_bf16 v[26:29], v[144:147], v[210:213], v[26:29]
	v_mfma_f32_16x16x32_bf16 v[18:21], v[154:157], v[210:213], v[18:21]
	v_mfma_f32_16x16x32_bf16 v[10:13], v[144:147], v[218:221], v[10:13]
	v_mfma_f32_16x16x32_bf16 v[6:9], v[154:157], v[218:221], v[6:9]
	s_setprio 0
	s_setprio 1
	v_mfma_f32_16x16x32_bf16 v[62:65], v[158:161], v[174:177], v[62:65]
	v_mfma_f32_16x16x32_bf16 v[54:57], v[166:169], v[174:177], v[54:57]
	v_mfma_f32_16x16x32_bf16 v[46:49], v[158:161], v[198:201], v[46:49]
	v_mfma_f32_16x16x32_bf16 v[38:41], v[166:169], v[198:201], v[38:41]
	v_mfma_f32_16x16x32_bf16 v[30:33], v[158:161], v[206:209], v[30:33]
	v_mfma_f32_16x16x32_bf16 v[22:25], v[166:169], v[206:209], v[22:25]
	v_mfma_f32_16x16x32_bf16 v[14:17], v[158:161], v[214:217], v[14:17]
	v_mfma_f32_16x16x32_bf16 v[2:5], v[166:169], v[214:217], v[2:5]
	v_mfma_f32_16x16x32_bf16 v[62:65], v[162:165], v[194:197], v[62:65]
	v_mfma_f32_16x16x32_bf16 v[54:57], v[170:173], v[194:197], v[54:57]
	v_mfma_f32_16x16x32_bf16 v[46:49], v[162:165], v[202:205], v[46:49]
	v_mfma_f32_16x16x32_bf16 v[38:41], v[170:173], v[202:205], v[38:41]
	v_mfma_f32_16x16x32_bf16 v[30:33], v[162:165], v[210:213], v[30:33]
	v_mfma_f32_16x16x32_bf16 v[22:25], v[170:173], v[210:213], v[22:25]
	v_mfma_f32_16x16x32_bf16 v[14:17], v[162:165], v[218:221], v[14:17]
	v_mfma_f32_16x16x32_bf16 v[2:5], v[170:173], v[218:221], v[2:5]
	s_setprio 0
	s_barrier
	s_add_i32 s79, s79, 2
	s_add_u32 s44, s44, 0x100
	s_addc_u32 s45, s45, 0
	s_add_u32 s76, s76, 0x100
	s_addc_u32 s77, s77, 0
	s_cmp_gt_u32 s79, 13
	s_cbranch_scc0 .LBB0_212
	s_branch .Lpeel_gu_after
	.p2align	6
